# hoist the small_gemm<1,1,4,2> prologue (first three K stages by LDS-DMA) to the start of the last unit's epilogue in out-proj, Q, Wo and MLP-down
# speedup vs baseline: 1.0126x; 1.0126x over previous
; template <int RA, int NP, int NS, int KT, class R8>
; DI void small_gemm(LAS unsigned char* lds, const bf16* __restrict__ A, const bf16* __restrict__ Bt, int K, int row_base, int col_base, const R8& e, int tid, int wave, int lane) {
;     ...
;     int R, Cc; pg8::stage_rc(tid * 16, R, Cc);
;     const int Rb = (R & ~31) + pg8::perm32(R & 31);
;     const bf16* asrc = A + (size_t)(row_base + R) * K + Cc;
;     const bf16* bsrc = Bt + (size_t)(col_base + Rb) * K + Cc;
;     const size_t bgrp = (size_t)64 * K;
;     const int NT = K / (64 * KT);
;     ...
; #pragma unroll
;     for (int s = 0; s < NS - 1; ++s) SG_STAGE(s, s);
.LBB0_982:
	s_cmp_lg_u32 s32, 0
	s_cbranch_scc0 .Lhoist0
	s_lshl_b32 s19, s3, 2
	s_andn2_b32 s19, s19, 63
	s_lshl_b32 s20, s34, 6
	v_and_b32_e32 v212, 0xffffffe0, v133
	v_or_b32_e32 v214, s19, v154
	s_lshl_b32 s21, s27, 7
	s_and_b32 s20, s20, 64
	v_and_b32_e32 v213, 24, v155
	v_add_u32_e32 v212, v214, v212
	s_or_b32 s21, s20, s21
	s_lshr_b32 s20, s42, 31
	v_or3_b32 v212, v212, v213, v153
	s_bitset1_b32 s21, 14
	s_add_i32 s20, s42, s20
	v_ashrrev_i32_e32 v213, 31, v212
	s_ashr_i32 s22, s20, 1
	v_add_u32_e32 v216, s21, v133
	v_lshlrev_b64 v[212:213], 11, v[212:213]
	v_ashrrev_i32_e32 v217, 31, v216
	v_lshl_add_u64 v[212:213], s[10:11], 0, v[212:213]
	s_lshl_b32 s23, s22, 4
	v_mov_b32_e32 v234, v132
	v_ashrrev_i32_e32 v235, 31, v132
	s_add_i32 s21, s21, s23
	v_lshlrev_b64 v[216:217], 11, v[216:217]
	v_lshlrev_b64 v[218:219], 1, v[234:235]
	v_or_b32_e32 v224, s21, v152
	v_lshl_add_u64 v[216:217], s[6:7], 0, v[216:217]
	s_add_i32 s21, s43, 0
	v_lshl_add_u64 v[230:231], v[216:217], 0, v[218:219]
	v_lshl_add_u64 v[228:229], v[212:213], 0, v[218:219]
	s_add_i32 m0, s21, 0x0
	s_nop 0
	global_load_lds_dwordx4 v[230:231], off
	s_add_i32 m0, s21, 0x2000
	s_nop 0
	global_load_lds_dwordx4 v[228:229], off
	v_lshl_add_u64 v[230:231], v[230:231], 0, s[52:53]
	v_lshl_add_u64 v[228:229], v[228:229], 0, s[52:53]
	s_add_i32 m0, s21, 0x4000
	s_nop 0
	global_load_lds_dwordx4 v[230:231], off
	s_add_i32 m0, s21, 0x6000
	s_nop 0
	global_load_lds_dwordx4 v[228:229], off
	v_lshl_add_u64 v[230:231], v[230:231], 0, s[52:53]
	v_lshl_add_u64 v[228:229], v[228:229], 0, s[52:53]
	s_add_i32 m0, s21, 0x8000
	s_nop 0
	global_load_lds_dwordx4 v[230:231], off
	s_add_i32 m0, s21, 0xa000
	s_nop 0
	global_load_lds_dwordx4 v[228:229], off
	v_lshl_add_u64 v[230:231], v[230:231], 0, s[52:53]
	v_lshl_add_u64 v[228:229], v[228:229], 0, s[52:53]
	s_add_i32 m0, s21, 0xc000
	s_nop 0
	global_load_lds_dwordx4 v[230:231], off
	s_add_i32 m0, s21, 0xe000
	s_nop 0
	global_load_lds_dwordx4 v[228:229], off
	v_lshl_add_u64 v[230:231], v[230:231], 0, s[52:53]
	v_lshl_add_u64 v[228:229], v[228:229], 0, s[52:53]
	s_add_i32 m0, s21, 0x10000
	s_nop 0
	global_load_lds_dwordx4 v[230:231], off
	s_add_i32 m0, s21, 0x12000
	s_nop 0
	global_load_lds_dwordx4 v[228:229], off
	v_lshl_add_u64 v[230:231], v[230:231], 0, s[52:53]
	v_lshl_add_u64 v[228:229], v[228:229], 0, s[52:53]
	s_add_i32 m0, s21, 0x14000
	s_nop 0
	global_load_lds_dwordx4 v[230:231], off
	s_add_i32 m0, s21, 0x16000
	s_nop 0
	global_load_lds_dwordx4 v[228:229], off

; template <int RA, int NP, int NS, int KT, class R8>
; DI void small_gemm(LAS unsigned char* lds, const bf16* __restrict__ A, const bf16* __restrict__ Bt, int K, int row_base, int col_base, const R8& e, int tid, int wave, int lane) {
;     ...
;     int R, Cc; pg8::stage_rc(tid * 16, R, Cc);
;     const int Rb = (R & ~31) + pg8::perm32(R & 31);
;     const bf16* asrc = A + (size_t)(row_base + R) * K + Cc;
;     const bf16* bsrc = Bt + (size_t)(col_base + Rb) * K + Cc;
;     const size_t bgrp = (size_t)64 * K;
;     const int NT = K / (64 * KT);
;     ...
;     const int r0 = row_base + 16 * (wr * RA), c0 = col_base + wc * (32 * NP);
;     float rsv[RA]; u32x4 prew[RA][NP];
; #pragma unroll
;     for (int ra = 0; ra < RA; ++ra) { rsv[ra] = 1.f; if constexpr (R8::NEED_RS) rsv[ra] = pg8::rs_of_row(e.SS, r0 + 16 * ra + fr, fq);
; #pragma unroll
;         for (int np = 0; np < NP; ++np) { prew[ra][np] = (u32x4){0u, 0u, 0u, 0u}; if constexpr (R8::HAS_PRE) prew[ra][np] = e.pre(r0 + 16 * ra + fr, c0 + 32 * np + 8 * fq); } }
;     f32x4 acc[RA][NP][2];
; #pragma unroll
;     for (int ra = 0; ra < RA; ++ra)
; #pragma unroll
;         for (int np = 0; np < NP; ++np) { acc[ra][np][0] = (f32x4){0.f, 0.f, 0.f, 0.f}; acc[ra][np][1] = (f32x4){0.f, 0.f, 0.f, 0.f}; }
;     int aoff[RA], boff[NP][2];
; #pragma unroll
;     for (int ra = 0; ra < RA; ++ra) aoff[ra] = pg8::lds_byte(16 * (wr * RA + ra) + fr, 8 * fq);
; #pragma unroll
;     for (int np = 0; np < NP; ++np)
; #pragma unroll
;         for (int n = 0; n < 2; ++n) { const int rb = wc * (32 * NP) + 32 * np + 16 * n + fr; boff[np][n] = 8192 * (1 + (rb >> 6)) + pg8::lds_byte(rb & 63, 8 * fq); }
; #pragma unroll
;     for (int s = 0; s < NS - 1; ++s) SG_STAGE(s, s);
.LBB0_1018:
	s_lshl_b32 s3, s3, 2
	s_andn2_b32 s3, s3, 63
	s_lshl_b32 s5, s34, 6
	v_and_b32_e32 v4, 0xffffffe0, v133
	v_or_b32_e32 v6, s3, v154
	s_lshl_b32 s4, s27, 7
	s_and_b32 s5, s5, 64
	v_and_b32_e32 v5, 24, v155
	v_add_u32_e32 v4, v6, v4
	s_or_b32 s4, s5, s4
	s_lshr_b32 s5, s42, 31
	v_or3_b32 v4, v4, v5, v153
	s_bitset1_b32 s4, 14
	s_add_i32 s5, s42, s5
	v_ashrrev_i32_e32 v5, 31, v4
	s_ashr_i32 s12, s5, 1
	v_add_u32_e32 v8, s4, v133
	v_lshlrev_b64 v[4:5], 11, v[4:5]
	v_ashrrev_i32_e32 v9, 31, v8
	v_lshl_add_u64 v[4:5], s[10:11], 0, v[4:5]
	s_lshl_b32 s10, s12, 4
	v_ashrrev_i32_e32 v133, 31, v132
	s_add_i32 s4, s4, s10
	v_lshlrev_b64 v[8:9], 11, v[8:9]
	v_lshlrev_b64 v[10:11], 1, v[132:133]
	v_or_b32_e32 v16, s4, v152
	v_lshl_add_u64 v[8:9], s[6:7], 0, v[8:9]
	s_add_i32 s4, s43, 0
	v_lshl_add_u64 v[22:23], v[8:9], 0, v[10:11]
	s_mov_b32 m0, s4
	v_lshl_add_u64 v[20:21], v[4:5], 0, v[10:11]
	s_nop 0
	s_add_i32 m0, s4, 0x2000
	v_lshl_add_u64 v[8:9], v[22:23], 0, s[52:53]
	s_nop 0
	s_add_i32 m0, s4, 0x4000
	s_mov_b64 s[6:7], 0x100
	s_nop 0
	v_lshl_add_u64 v[8:9], v[20:21], 0, s[52:53]
	s_add_i32 m0, s4, 0x6000
	s_and_b32 s5, s5, -2
	s_nop 0
	s_add_i32 m0, s4, 0x8000
	v_lshl_add_u64 v[8:9], v[22:23], 0, s[6:7]
	s_sub_i32 s5, s42, s5
	s_nop 0
	v_lshl_add_u64 v[8:9], v[20:21], 0, s[6:7]
	s_add_i32 m0, s4, 0xa000
	s_mov_b64 s[6:7], 0x180
	s_lshl_b32 s10, s5, 5
	s_nop 0
	v_lshl_add_u64 v[8:9], v[22:23], 0, s[6:7]
	s_add_i32 m0, s4, 0xc000
	s_add_i32 s3, s10, s3
	v_lshrrev_b32_e32 v4, 1, v3
	v_ashrrev_i32_e32 v17, 31, v16
	s_nop 0
	v_lshl_add_u64 v[8:9], v[20:21], 0, s[6:7]
	s_add_i32 m0, s4, 0xe000
	v_and_or_b32 v4, v4, 24, s3
	v_lshlrev_b64 v[6:7], 11, v[16:17]
	s_nop 0
	s_add_i32 m0, s4, 0x10000
	v_lshl_add_u64 v[8:9], v[22:23], 0, s[54:55]
	v_lshl_add_u64 v[6:7], s[8:9], 0, v[6:7]
	v_ashrrev_i32_e32 v5, 31, v4
	s_nop 0
	v_lshl_add_u64 v[8:9], v[20:21], 0, s[54:55]
	s_add_i32 m0, s4, 0x12000
	s_mov_b64 s[6:7], 0x280
	v_lshl_add_u64 v[18:19], v[4:5], 1, v[6:7]
	s_nop 0
	v_lshl_add_u64 v[8:9], v[22:23], 0, s[6:7]
	s_add_i32 m0, s4, 0x14000
	global_load_dwordx4 v[4:7], v[18:19], off
	v_and_b32_e32 v24, 63, v3
	s_nop 0
	v_lshl_add_u64 v[8:9], v[20:21], 0, s[6:7]
	s_add_i32 m0, s4, 0x16000
	v_lshlrev_b32_e32 v11, 6, v3
	s_nop 0
	v_and_b32_e32 v8, 48, v3
	v_lshlrev_b32_e32 v3, 2, v3
	v_lshlrev_b32_e32 v10, 2, v152
	s_and_b32 s6, s5, 0xffffe000
	v_and_b32_e32 v11, 0x3c0, v11
	s_lshl_b32 s5, s5, 12
	v_and_b32_e32 v3, 32, v3
	v_lshlrev_b32_e32 v9, 6, v152
	v_and_b32_e32 v10, 32, v10
	s_and_b32 s5, s5, 0x1000
	v_bitop3_b32 v3, v11, v3, v8 bitop3:0x36
	v_or_b32_e32 v11, s5, v3
	v_bitop3_b32 v3, v9, v10, v8 bitop3:0x36
	v_mov_b32_e32 v8, 0
	s_lshl_b32 s5, s12, 11
	v_or_b32_e32 v25, s6, v11
	s_movk_i32 s6, 0x180
	s_mov_b32 s7, 0
	v_mov_b32_e32 v9, v8
	v_mov_b32_e32 v10, v8
	v_mov_b32_e32 v11, v8
	v_mov_b32_e32 v12, v8
	v_mov_b32_e32 v13, v8
	v_mov_b32_e32 v14, v8
	v_mov_b32_e32 v15, v8

; template <int RA, int NP, int NS, int KT, class R8>
; DI void small_gemm(LAS unsigned char* lds, const bf16* __restrict__ A, const bf16* __restrict__ Bt, int K, int row_base, int col_base, const R8& e, int tid, int wave, int lane) {
;     ...
;     int R, Cc; pg8::stage_rc(tid * 16, R, Cc);
;     const int Rb = (R & ~31) + pg8::perm32(R & 31);
;     const bf16* asrc = A + (size_t)(row_base + R) * K + Cc;
;     const bf16* bsrc = Bt + (size_t)(col_base + Rb) * K + Cc;
;     const size_t bgrp = (size_t)64 * K;
;     const int NT = K / (64 * KT);
;     ...
;     const int r0 = row_base + 16 * (wr * RA), c0 = col_base + wc * (32 * NP);
;     float rsv[RA]; u32x4 prew[RA][NP];
; #pragma unroll
;     for (int ra = 0; ra < RA; ++ra) { rsv[ra] = 1.f; if constexpr (R8::NEED_RS) rsv[ra] = pg8::rs_of_row(e.SS, r0 + 16 * ra + fr, fq);
; #pragma unroll
;         for (int np = 0; np < NP; ++np) { prew[ra][np] = (u32x4){0u, 0u, 0u, 0u}; if constexpr (R8::HAS_PRE) prew[ra][np] = e.pre(r0 + 16 * ra + fr, c0 + 32 * np + 8 * fq); } }
;     ...
; #pragma unroll
;     for (int s = 0; s < NS - 1; ++s) SG_STAGE(s, s);
.LBB0_1111:
	s_cmp_lg_u32 s32, 0
	s_cbranch_scc0 .Lhoist1
	s_lshl_b32 s18, s62, 6
	s_lshl_b32 s19, s3, 7
	s_and_b32 s18, s18, 64
	s_or_b32 s19, s18, s19
	s_or_b32 s20, s19, 0x4000
	s_lshl_b32 s19, s27, 2
	v_add_u32_e32 v212, s20, v133
	s_and_b32 s18, s19, 0xffffffc0
	v_ashrrev_i32_e32 v213, 31, v212
	v_and_b32_e32 v214, 0xffffffe0, v133
	v_lshlrev_b64 v[220:221], 11, v[212:213]
	v_or_b32_e32 v212, s18, v154
	v_and_b32_e32 v215, 24, v155
	v_add_u32_e32 v212, v212, v214
	s_ashr_i32 s21, s34, 6
	s_lshr_b32 s22, s34, 31
	v_or3_b32 v212, v212, v215, v153
	s_add_i32 s22, s21, s22
	v_ashrrev_i32_e32 v213, 31, v212
	s_ashr_i32 s23, s22, 1
	v_lshlrev_b64 v[212:213], 11, v[212:213]
	v_lshl_add_u64 v[222:223], s[12:13], 0, v[212:213]
	s_lshl_b32 s24, s23, 4
	s_add_i32 s20, s20, s24
	v_or_b32_e32 v228, s20, v152
	v_ashrrev_i32_e32 v229, 31, v228
	v_lshlrev_b64 v[212:213], 7, v[228:229]
	v_mov_b32_e32 v234, v132
	v_ashrrev_i32_e32 v235, 31, v132
	v_lshl_add_u64 v[212:213], s[4:5], 0, v[212:213]
	s_lshl_b32 s25, s21, 10
	v_lshlrev_b32_e32 v214, 2, v151
	v_mov_b32_e32 v215, v2
	v_lshl_add_u64 v[220:221], s[8:9], 0, v[220:221]
	v_lshlrev_b64 v[224:225], 1, v[234:235]
	s_add_i32 s25, s25, 0
	v_lshl_add_u64 v[216:217], v[212:213], 0, v[214:215]
	v_lshl_add_u64 v[232:233], v[220:221], 0, v[224:225]
	v_lshl_add_u64 v[230:231], v[222:223], 0, v[224:225]
	s_add_i32 m0, s25, 0x0
	s_nop 0
	global_load_lds_dwordx4 v[232:233], off
	s_add_i32 m0, s25, 0x2000
	s_nop 0
	global_load_lds_dwordx4 v[230:231], off
	v_lshl_add_u64 v[232:233], v[232:233], 0, s[52:53]
	v_lshl_add_u64 v[230:231], v[230:231], 0, s[52:53]
	s_add_i32 m0, s25, 0x4000
	s_nop 0
	global_load_lds_dwordx4 v[232:233], off
	s_add_i32 m0, s25, 0x6000
	s_nop 0
	global_load_lds_dwordx4 v[230:231], off
	v_lshl_add_u64 v[232:233], v[232:233], 0, s[52:53]
	v_lshl_add_u64 v[230:231], v[230:231], 0, s[52:53]
	s_add_i32 m0, s25, 0x8000
	s_nop 0
	global_load_lds_dwordx4 v[232:233], off
	s_add_i32 m0, s25, 0xa000
	s_nop 0
	global_load_lds_dwordx4 v[230:231], off
	v_lshl_add_u64 v[232:233], v[232:233], 0, s[52:53]
	v_lshl_add_u64 v[230:231], v[230:231], 0, s[52:53]
	s_add_i32 m0, s25, 0xc000
	s_nop 0
	global_load_lds_dwordx4 v[232:233], off
	s_add_i32 m0, s25, 0xe000
	s_nop 0
	global_load_lds_dwordx4 v[230:231], off
	v_lshl_add_u64 v[232:233], v[232:233], 0, s[52:53]
	v_lshl_add_u64 v[230:231], v[230:231], 0, s[52:53]
	s_add_i32 m0, s25, 0x10000
	s_nop 0
	global_load_lds_dwordx4 v[232:233], off
	s_add_i32 m0, s25, 0x12000
	s_nop 0
	global_load_lds_dwordx4 v[230:231], off
	v_lshl_add_u64 v[232:233], v[232:233], 0, s[52:53]
	v_lshl_add_u64 v[230:231], v[230:231], 0, s[52:53]
	s_add_i32 m0, s25, 0x14000
	s_nop 0
	global_load_lds_dwordx4 v[232:233], off
	s_add_i32 m0, s25, 0x16000
	s_nop 0
	global_load_lds_dwordx4 v[230:231], off

; template <int RA, int NP, int NS, int KT, class R8>
; DI void small_gemm(LAS unsigned char* lds, const bf16* __restrict__ A, const bf16* __restrict__ Bt, int K, int row_base, int col_base, const R8& e, int tid, int wave, int lane) {
;     ...
;     int R, Cc; pg8::stage_rc(tid * 16, R, Cc);
;     const int Rb = (R & ~31) + pg8::perm32(R & 31);
;     const bf16* asrc = A + (size_t)(row_base + R) * K + Cc;
;     const bf16* bsrc = Bt + (size_t)(col_base + Rb) * K + Cc;
;     const size_t bgrp = (size_t)64 * K;
;     const int NT = K / (64 * KT);
;     ...
;     const int r0 = row_base + 16 * (wr * RA), c0 = col_base + wc * (32 * NP);
;     float rsv[RA]; u32x4 prew[RA][NP];
; #pragma unroll
;     for (int ra = 0; ra < RA; ++ra) { rsv[ra] = 1.f; if constexpr (R8::NEED_RS) rsv[ra] = pg8::rs_of_row(e.SS, r0 + 16 * ra + fr, fq);
; #pragma unroll
;         for (int np = 0; np < NP; ++np) { prew[ra][np] = (u32x4){0u, 0u, 0u, 0u}; if constexpr (R8::HAS_PRE) prew[ra][np] = e.pre(r0 + 16 * ra + fr, c0 + 32 * np + 8 * fq); } }
;     f32x4 acc[RA][NP][2];
; #pragma unroll
;     for (int ra = 0; ra < RA; ++ra)
; #pragma unroll
;         for (int np = 0; np < NP; ++np) { acc[ra][np][0] = (f32x4){0.f, 0.f, 0.f, 0.f}; acc[ra][np][1] = (f32x4){0.f, 0.f, 0.f, 0.f}; }
;     int aoff[RA], boff[NP][2];
; #pragma unroll
;     for (int ra = 0; ra < RA; ++ra) aoff[ra] = pg8::lds_byte(16 * (wr * RA + ra) + fr, 8 * fq);
; #pragma unroll
;     for (int np = 0; np < NP; ++np)
; #pragma unroll
;         for (int n = 0; n < 2; ++n) { const int rb = wc * (32 * NP) + 32 * np + 16 * n + fr; boff[np][n] = 8192 * (1 + (rb >> 6)) + pg8::lds_byte(rb & 63, 8 * fq); }
; #pragma unroll
;     for (int s = 0; s < NS - 1; ++s) SG_STAGE(s, s);
.LBB0_1115:
	s_lshl_b32 s17, s62, 6
	s_lshl_b32 s16, s3, 7
	s_and_b32 s17, s17, 64
	s_or_b32 s16, s17, s16
	s_or_b32 s19, s16, 0x4000
	s_lshl_b32 s16, s27, 2
	v_add_u32_e32 v4, s19, v133
	s_and_b32 s17, s16, 0xffffffc0
	v_ashrrev_i32_e32 v5, 31, v4
	v_and_b32_e32 v6, 0xffffffe0, v133
	v_lshlrev_b64 v[12:13], 11, v[4:5]
	v_or_b32_e32 v4, s17, v154
	v_and_b32_e32 v7, 24, v155
	v_add_u32_e32 v4, v4, v6
	s_ashr_i32 s18, s34, 6
	s_lshr_b32 s20, s34, 31
	v_or3_b32 v4, v4, v7, v153
	s_add_i32 s20, s18, s20
	v_ashrrev_i32_e32 v5, 31, v4
	s_ashr_i32 s21, s20, 1
	v_lshlrev_b64 v[4:5], 11, v[4:5]
	v_lshl_add_u64 v[14:15], s[12:13], 0, v[4:5]
	s_lshl_b32 s12, s21, 4
	s_add_i32 s19, s19, s12
	v_or_b32_e32 v20, s19, v152
	v_ashrrev_i32_e32 v21, 31, v20
	v_lshlrev_b64 v[4:5], 7, v[20:21]
	v_ashrrev_i32_e32 v133, 31, v132
	v_lshl_add_u64 v[4:5], s[4:5], 0, v[4:5]
	s_lshl_b32 s4, s18, 10
	v_lshlrev_b32_e32 v6, 2, v151
	v_mov_b32_e32 v7, v2
	v_lshl_add_u64 v[12:13], s[8:9], 0, v[12:13]
	v_lshlrev_b64 v[16:17], 1, v[132:133]
	s_add_i32 s4, s4, 0
	v_lshl_add_u64 v[8:9], v[4:5], 0, v[6:7]
	v_lshl_add_u64 v[24:25], v[12:13], 0, v[16:17]
	s_mov_b32 m0, s4
	global_load_dwordx4 v[4:7], v[8:9], off offset:16
	s_nop 0
	global_load_dwordx4 v[8:11], v[8:9], off
	v_lshl_add_u64 v[22:23], v[14:15], 0, v[16:17]
	s_nop 0
	s_add_i32 m0, s4, 0x2000
	v_lshl_add_u64 v[12:13], v[24:25], 0, s[52:53]
	s_nop 0
	s_add_i32 m0, s4, 0x4000
	s_mov_b64 s[8:9], 0x100
	s_nop 0
	v_lshl_add_u64 v[12:13], v[22:23], 0, s[52:53]
	s_add_i32 m0, s4, 0x6000
	s_and_b32 s5, s20, -2
	s_nop 0
	s_add_i32 m0, s4, 0x8000
	v_lshl_add_u64 v[12:13], v[24:25], 0, s[8:9]
	s_nop 0
	v_lshl_add_u64 v[12:13], v[22:23], 0, s[8:9]
	s_add_i32 m0, s4, 0xa000
	s_mov_b64 s[8:9], 0x180
	s_nop 0
	v_lshl_add_u64 v[12:13], v[24:25], 0, s[8:9]
	s_add_i32 m0, s4, 0xc000
	s_sub_i32 s5, s18, s5
	s_nop 0
	v_lshl_add_u64 v[12:13], v[22:23], 0, s[8:9]
	s_add_i32 m0, s4, 0xe000
	s_mov_b64 s[8:9], 0x280
	s_nop 0
	s_add_i32 m0, s4, 0x10000
	v_lshl_add_u64 v[12:13], v[24:25], 0, s[54:55]
	s_nop 0
	v_lshl_add_u64 v[12:13], v[22:23], 0, s[54:55]
	s_add_i32 m0, s4, 0x12000
	v_lshlrev_b32_e32 v15, 6, v3
	s_nop 0
	v_lshl_add_u64 v[12:13], v[24:25], 0, s[8:9]
	s_add_i32 m0, s4, 0x14000
	v_lshlrev_b32_e32 v16, 2, v3
	s_nop 0
	v_lshl_add_u64 v[12:13], v[22:23], 0, s[8:9]
	s_add_i32 m0, s4, 0x16000
	v_lshlrev_b32_e32 v14, 2, v152
	s_nop 0
	v_and_b32_e32 v12, 48, v3
	v_and_b32_e32 v15, 0x3c0, v15
	s_lshl_b32 s12, s5, 12
	v_and_b32_e32 v16, 32, v16
	v_lshlrev_b32_e32 v13, 6, v152
	v_and_b32_e32 v14, 32, v14
	s_and_b32 s12, s12, 0x1000
	v_bitop3_b32 v15, v15, v16, v12 bitop3:0x36
	s_and_b32 s13, s5, 0xffffe000
	v_or_b32_e32 v15, s12, v15
	v_bitop3_b32 v26, v13, v14, v12 bitop3:0x36
	v_mov_b32_e32 v12, 0
	s_lshl_b64 s[8:9], s[6:7], 20
	s_lshl_b32 s12, s21, 11
	v_or_b32_e32 v27, s13, v15
	s_movk_i32 s13, 0x180
	s_mov_b32 s18, 0
	v_mov_b32_e32 v13, v12
	v_mov_b32_e32 v14, v12
	v_mov_b32_e32 v15, v12
	v_mov_b32_e32 v16, v12
	v_mov_b32_e32 v17, v12
	v_mov_b32_e32 v18, v12
	v_mov_b32_e32 v19, v12

; template <int RA, int NP, int NS, int KT, class R8>
; DI void small_gemm(LAS unsigned char* lds, const bf16* __restrict__ A, const bf16* __restrict__ Bt, int K, int row_base, int col_base, const R8& e, int tid, int wave, int lane) {
;     ...
;     int R, Cc; pg8::stage_rc(tid * 16, R, Cc);
;     const int Rb = (R & ~31) + pg8::perm32(R & 31);
;     const bf16* asrc = A + (size_t)(row_base + R) * K + Cc;
;     const bf16* bsrc = Bt + (size_t)(col_base + Rb) * K + Cc;
;     const size_t bgrp = (size_t)64 * K;
;     const int NT = K / (64 * KT);
;     ...
; #pragma unroll
;     for (int s = 0; s < NS - 1; ++s) SG_STAGE(s, s);
.LBB0_1269:
	s_cmp_lg_u32 s32, 0
	s_cbranch_scc0 .Lhoist2
	s_lshl_b32 s16, s3, 2
	s_andn2_b32 s16, s16, 63
	s_lshl_b32 s17, s34, 6
	v_and_b32_e32 v212, 0xffffffe0, v133
	v_or_b32_e32 v214, s16, v154
	s_lshl_b32 s21, s27, 7
	s_and_b32 s17, s17, 64
	v_and_b32_e32 v213, 24, v155
	v_add_u32_e32 v212, v214, v212
	s_or_b32 s21, s17, s21
	s_lshr_b32 s17, s54, 31
	v_or3_b32 v212, v212, v213, v153
	s_bitset1_b32 s21, 14
	s_add_i32 s17, s54, s17
	v_ashrrev_i32_e32 v213, 31, v212
	s_ashr_i32 s22, s17, 1
	v_add_u32_e32 v216, s21, v133
	v_lshlrev_b64 v[212:213], 11, v[212:213]
	v_ashrrev_i32_e32 v217, 31, v216
	v_lshl_add_u64 v[212:213], s[12:13], 0, v[212:213]
	s_lshl_b32 s23, s22, 4
	v_mov_b32_e32 v234, v132
	v_ashrrev_i32_e32 v235, 31, v132
	s_add_i32 s21, s21, s23
	v_lshlrev_b64 v[216:217], 11, v[216:217]
	v_lshlrev_b64 v[218:219], 1, v[234:235]
	v_or_b32_e32 v224, s21, v152
	v_lshl_add_u64 v[216:217], s[8:9], 0, v[216:217]
	s_add_i32 s21, s55, 0
	v_lshl_add_u64 v[230:231], v[216:217], 0, v[218:219]
	v_lshl_add_u64 v[228:229], v[212:213], 0, v[218:219]
	s_add_i32 m0, s21, 0x0
	s_nop 0
	global_load_lds_dwordx4 v[230:231], off
	s_add_i32 m0, s21, 0x2000
	s_nop 0
	global_load_lds_dwordx4 v[228:229], off
	v_lshl_add_u64 v[230:231], v[230:231], 0, s[52:53]
	v_lshl_add_u64 v[228:229], v[228:229], 0, s[52:53]
	s_add_i32 m0, s21, 0x4000
	s_nop 0
	global_load_lds_dwordx4 v[230:231], off
	s_add_i32 m0, s21, 0x6000
	s_nop 0
	global_load_lds_dwordx4 v[228:229], off
	v_lshl_add_u64 v[230:231], v[230:231], 0, s[52:53]
	v_lshl_add_u64 v[228:229], v[228:229], 0, s[52:53]
	s_add_i32 m0, s21, 0x8000
	s_nop 0
	global_load_lds_dwordx4 v[230:231], off
	s_add_i32 m0, s21, 0xa000
	s_nop 0
	global_load_lds_dwordx4 v[228:229], off
	v_lshl_add_u64 v[230:231], v[230:231], 0, s[52:53]
	v_lshl_add_u64 v[228:229], v[228:229], 0, s[52:53]
	s_add_i32 m0, s21, 0xc000
	s_nop 0
	global_load_lds_dwordx4 v[230:231], off
	s_add_i32 m0, s21, 0xe000
	s_nop 0
	global_load_lds_dwordx4 v[228:229], off
	v_lshl_add_u64 v[230:231], v[230:231], 0, s[52:53]
	v_lshl_add_u64 v[228:229], v[228:229], 0, s[52:53]
	s_add_i32 m0, s21, 0x10000
	s_nop 0
	global_load_lds_dwordx4 v[230:231], off
	s_add_i32 m0, s21, 0x12000
	s_nop 0
	global_load_lds_dwordx4 v[228:229], off
	v_lshl_add_u64 v[230:231], v[230:231], 0, s[52:53]
	v_lshl_add_u64 v[228:229], v[228:229], 0, s[52:53]
	s_add_i32 m0, s21, 0x14000
	s_nop 0
	global_load_lds_dwordx4 v[230:231], off
	s_add_i32 m0, s21, 0x16000
	s_nop 0
	global_load_lds_dwordx4 v[228:229], off

; template <int RA, int NP, int NS, int KT, class R8>
; DI void small_gemm(LAS unsigned char* lds, const bf16* __restrict__ A, const bf16* __restrict__ Bt, int K, int row_base, int col_base, const R8& e, int tid, int wave, int lane) {
;     ...
;     int R, Cc; pg8::stage_rc(tid * 16, R, Cc);
;     const int Rb = (R & ~31) + pg8::perm32(R & 31);
;     const bf16* asrc = A + (size_t)(row_base + R) * K + Cc;
;     const bf16* bsrc = Bt + (size_t)(col_base + Rb) * K + Cc;
;     const size_t bgrp = (size_t)64 * K;
;     const int NT = K / (64 * KT);
;     ...
;     const int r0 = row_base + 16 * (wr * RA), c0 = col_base + wc * (32 * NP);
;     float rsv[RA]; u32x4 prew[RA][NP];
; #pragma unroll
;     for (int ra = 0; ra < RA; ++ra) { rsv[ra] = 1.f; if constexpr (R8::NEED_RS) rsv[ra] = pg8::rs_of_row(e.SS, r0 + 16 * ra + fr, fq);
; #pragma unroll
;         for (int np = 0; np < NP; ++np) { prew[ra][np] = (u32x4){0u, 0u, 0u, 0u}; if constexpr (R8::HAS_PRE) prew[ra][np] = e.pre(r0 + 16 * ra + fr, c0 + 32 * np + 8 * fq); } }
;     f32x4 acc[RA][NP][2];
; #pragma unroll
;     for (int ra = 0; ra < RA; ++ra)
; #pragma unroll
;         for (int np = 0; np < NP; ++np) { acc[ra][np][0] = (f32x4){0.f, 0.f, 0.f, 0.f}; acc[ra][np][1] = (f32x4){0.f, 0.f, 0.f, 0.f}; }
;     int aoff[RA], boff[NP][2];
; #pragma unroll
;     for (int ra = 0; ra < RA; ++ra) aoff[ra] = pg8::lds_byte(16 * (wr * RA + ra) + fr, 8 * fq);
; #pragma unroll
;     for (int np = 0; np < NP; ++np)
; #pragma unroll
;         for (int n = 0; n < 2; ++n) { const int rb = wc * (32 * NP) + 32 * np + 16 * n + fr; boff[np][n] = 8192 * (1 + (rb >> 6)) + pg8::lds_byte(rb & 63, 8 * fq); }
; #pragma unroll
;     for (int s = 0; s < NS - 1; ++s) SG_STAGE(s, s);
.LBB0_1305:
	s_lshl_b32 s3, s3, 2
	s_andn2_b32 s3, s3, 63
	s_lshl_b32 s5, s34, 6
	v_and_b32_e32 v4, 0xffffffe0, v133
	v_or_b32_e32 v6, s3, v154
	s_lshl_b32 s4, s27, 7
	s_and_b32 s5, s5, 64
	v_and_b32_e32 v5, 24, v155
	v_add_u32_e32 v4, v6, v4
	s_or_b32 s4, s5, s4
	s_lshr_b32 s5, s54, 31
	v_or3_b32 v4, v4, v5, v153
	s_bitset1_b32 s4, 14
	s_add_i32 s5, s54, s5
	v_ashrrev_i32_e32 v5, 31, v4
	s_ashr_i32 s14, s5, 1
	v_add_u32_e32 v8, s4, v133
	v_lshlrev_b64 v[4:5], 11, v[4:5]
	v_ashrrev_i32_e32 v9, 31, v8
	v_lshl_add_u64 v[4:5], s[12:13], 0, v[4:5]
	s_lshl_b32 s12, s14, 4
	v_ashrrev_i32_e32 v133, 31, v132
	s_add_i32 s4, s4, s12
	v_lshlrev_b64 v[8:9], 11, v[8:9]
	v_lshlrev_b64 v[10:11], 1, v[132:133]
	v_or_b32_e32 v16, s4, v152
	v_lshl_add_u64 v[8:9], s[8:9], 0, v[8:9]
	s_add_i32 s4, s55, 0
	v_lshl_add_u64 v[22:23], v[8:9], 0, v[10:11]
	s_mov_b32 m0, s4
	v_lshl_add_u64 v[20:21], v[4:5], 0, v[10:11]
	s_nop 0
	s_add_i32 m0, s4, 0x2000
	v_lshl_add_u64 v[8:9], v[22:23], 0, s[52:53]
	s_nop 0
	s_add_i32 m0, s4, 0x4000
	s_mov_b64 s[8:9], 0x100
	s_nop 0
	v_lshl_add_u64 v[8:9], v[20:21], 0, s[52:53]
	s_add_i32 m0, s4, 0x6000
	s_and_b32 s5, s5, -2
	s_nop 0
	s_add_i32 m0, s4, 0x8000
	v_lshl_add_u64 v[8:9], v[22:23], 0, s[8:9]
	s_sub_i32 s5, s54, s5
	s_nop 0
	v_lshl_add_u64 v[8:9], v[20:21], 0, s[8:9]
	s_add_i32 m0, s4, 0xa000
	s_mov_b64 s[8:9], 0x180
	s_lshl_b32 s12, s5, 5
	s_nop 0
	v_lshl_add_u64 v[8:9], v[22:23], 0, s[8:9]
	s_add_i32 m0, s4, 0xc000
	s_add_i32 s3, s12, s3
	v_lshrrev_b32_e32 v4, 1, v3
	v_ashrrev_i32_e32 v17, 31, v16
	s_nop 0
	v_lshl_add_u64 v[8:9], v[20:21], 0, s[8:9]
	s_add_i32 m0, s4, 0xe000
	s_mov_b64 s[54:55], 0x200
	v_and_or_b32 v4, v4, 24, s3
	v_lshlrev_b64 v[6:7], 11, v[16:17]
	s_nop 0
	s_add_i32 m0, s4, 0x10000
	v_lshl_add_u64 v[8:9], v[22:23], 0, s[54:55]
	v_lshl_add_u64 v[6:7], s[10:11], 0, v[6:7]
	v_ashrrev_i32_e32 v5, 31, v4
	s_nop 0
	v_lshl_add_u64 v[8:9], v[20:21], 0, s[54:55]
	s_add_i32 m0, s4, 0x12000
	s_mov_b64 s[8:9], 0x280
	v_lshl_add_u64 v[18:19], v[4:5], 1, v[6:7]
	s_nop 0
	v_lshl_add_u64 v[8:9], v[22:23], 0, s[8:9]
	s_add_i32 m0, s4, 0x14000
	global_load_dwordx4 v[4:7], v[18:19], off
	v_and_b32_e32 v24, 63, v3
	s_nop 0
	v_lshl_add_u64 v[8:9], v[20:21], 0, s[8:9]
	s_add_i32 m0, s4, 0x16000
	v_lshlrev_b32_e32 v11, 6, v3
	s_nop 0
	v_and_b32_e32 v8, 48, v3
	v_lshlrev_b32_e32 v3, 2, v3
	v_lshlrev_b32_e32 v10, 2, v152
	s_and_b32 s8, s5, 0xffffe000
	v_and_b32_e32 v11, 0x3c0, v11
	s_lshl_b32 s5, s5, 12
	v_and_b32_e32 v3, 32, v3
	v_lshlrev_b32_e32 v9, 6, v152
	v_and_b32_e32 v10, 32, v10
	s_and_b32 s5, s5, 0x1000
	v_bitop3_b32 v3, v11, v3, v8 bitop3:0x36
	v_or_b32_e32 v11, s5, v3
	v_bitop3_b32 v3, v9, v10, v8 bitop3:0x36
	v_mov_b32_e32 v8, 0
	s_lshl_b32 s5, s14, 11
	v_or_b32_e32 v25, s8, v11
	s_movk_i32 s8, 0x180
	s_mov_b32 s9, 0
	v_mov_b32_e32 v9, v8
	v_mov_b32_e32 v10, v8
	v_mov_b32_e32 v11, v8
	v_mov_b32_e32 v12, v8
	v_mov_b32_e32 v13, v8
	v_mov_b32_e32 v14, v8
	v_mov_b32_e32 v15, v8

; template <int RA, int NP, int NS, int KT, class R8>
; DI void small_gemm(LAS unsigned char* lds, const bf16* __restrict__ A, const bf16* __restrict__ Bt, int K, int row_base, int col_base, const R8& e, int tid, int wave, int lane) {
;     ...
;     int R, Cc; pg8::stage_rc(tid * 16, R, Cc);
;     const int Rb = (R & ~31) + pg8::perm32(R & 31);
;     const bf16* asrc = A + (size_t)(row_base + R) * K + Cc;
;     const bf16* bsrc = Bt + (size_t)(col_base + Rb) * K + Cc;
;     const size_t bgrp = (size_t)64 * K;
;     const int NT = K / (64 * KT);
;     ...
; #pragma unroll
;     for (int s = 0; s < NS - 1; ++s) SG_STAGE(s, s);
.LBB0_1463:
	s_cmp_lg_u32 s32, 0
	s_cbranch_scc0 .Lhoist3
	s_lshl_b32 s19, s3, 2
	s_andn2_b32 s19, s19, 63
	s_lshl_b32 s20, s34, 6
	v_and_b32_e32 v212, 0xffffffe0, v133
	v_or_b32_e32 v214, s19, v154
	s_lshl_b32 s21, s27, 7
	s_and_b32 s20, s20, 64
	v_and_b32_e32 v213, 24, v155
	v_add_u32_e32 v212, v214, v212
	s_or_b32 s21, s20, s21
	s_lshr_b32 s20, s42, 31
	v_or3_b32 v212, v212, v213, v153
	s_bitset1_b32 s21, 14
	s_add_i32 s20, s42, s20
	v_ashrrev_i32_e32 v213, 31, v212
	s_ashr_i32 s22, s20, 1
	v_add_u32_e32 v216, s21, v133
	v_lshlrev_b64 v[212:213], 13, v[212:213]
	v_ashrrev_i32_e32 v217, 31, v216
	v_lshl_add_u64 v[212:213], s[10:11], 0, v[212:213]
	s_lshl_b32 s23, s22, 4
	v_mov_b32_e32 v234, v132
	v_ashrrev_i32_e32 v235, 31, v132
	s_add_i32 s21, s21, s23
	v_lshlrev_b64 v[216:217], 13, v[216:217]
	v_lshlrev_b64 v[218:219], 1, v[234:235]
	v_or_b32_e32 v224, s21, v152
	v_lshl_add_u64 v[216:217], s[6:7], 0, v[216:217]
	s_add_i32 s21, s43, 0
	v_lshl_add_u64 v[230:231], v[216:217], 0, v[218:219]
	v_lshl_add_u64 v[228:229], v[212:213], 0, v[218:219]
	s_add_i32 m0, s21, 0x0
	s_nop 0
	global_load_lds_dwordx4 v[230:231], off
	s_add_i32 m0, s21, 0x2000
	s_nop 0
	global_load_lds_dwordx4 v[228:229], off
	v_lshl_add_u64 v[230:231], v[230:231], 0, s[52:53]
	v_lshl_add_u64 v[228:229], v[228:229], 0, s[52:53]
	s_add_i32 m0, s21, 0x4000
	s_nop 0
	global_load_lds_dwordx4 v[230:231], off
	s_add_i32 m0, s21, 0x6000
	s_nop 0
	global_load_lds_dwordx4 v[228:229], off
	v_lshl_add_u64 v[230:231], v[230:231], 0, s[52:53]
	v_lshl_add_u64 v[228:229], v[228:229], 0, s[52:53]
	s_add_i32 m0, s21, 0x8000
	s_nop 0
	global_load_lds_dwordx4 v[230:231], off
	s_add_i32 m0, s21, 0xa000
	s_nop 0
	global_load_lds_dwordx4 v[228:229], off
	v_lshl_add_u64 v[230:231], v[230:231], 0, s[52:53]
	v_lshl_add_u64 v[228:229], v[228:229], 0, s[52:53]
	s_add_i32 m0, s21, 0xc000
	s_nop 0
	global_load_lds_dwordx4 v[230:231], off
	s_add_i32 m0, s21, 0xe000
	s_nop 0
	global_load_lds_dwordx4 v[228:229], off
	v_lshl_add_u64 v[230:231], v[230:231], 0, s[52:53]
	v_lshl_add_u64 v[228:229], v[228:229], 0, s[52:53]
	s_add_i32 m0, s21, 0x10000
	s_nop 0
	global_load_lds_dwordx4 v[230:231], off
	s_add_i32 m0, s21, 0x12000
	s_nop 0
	global_load_lds_dwordx4 v[228:229], off
	v_lshl_add_u64 v[230:231], v[230:231], 0, s[52:53]
	v_lshl_add_u64 v[228:229], v[228:229], 0, s[52:53]
	s_add_i32 m0, s21, 0x14000
	s_nop 0
	global_load_lds_dwordx4 v[230:231], off
	s_add_i32 m0, s21, 0x16000
	s_nop 0
	global_load_lds_dwordx4 v[228:229], off

; template <int RA, int NP, int NS, int KT, class R8>
; DI void small_gemm(LAS unsigned char* lds, const bf16* __restrict__ A, const bf16* __restrict__ Bt, int K, int row_base, int col_base, const R8& e, int tid, int wave, int lane) {
;     ...
;     int R, Cc; pg8::stage_rc(tid * 16, R, Cc);
;     const int Rb = (R & ~31) + pg8::perm32(R & 31);
;     const bf16* asrc = A + (size_t)(row_base + R) * K + Cc;
;     const bf16* bsrc = Bt + (size_t)(col_base + Rb) * K + Cc;
;     const size_t bgrp = (size_t)64 * K;
;     const int NT = K / (64 * KT);
;     ...
;     const int r0 = row_base + 16 * (wr * RA), c0 = col_base + wc * (32 * NP);
;     float rsv[RA]; u32x4 prew[RA][NP];
; #pragma unroll
;     for (int ra = 0; ra < RA; ++ra) { rsv[ra] = 1.f; if constexpr (R8::NEED_RS) rsv[ra] = pg8::rs_of_row(e.SS, r0 + 16 * ra + fr, fq);
; #pragma unroll
;         for (int np = 0; np < NP; ++np) { prew[ra][np] = (u32x4){0u, 0u, 0u, 0u}; if constexpr (R8::HAS_PRE) prew[ra][np] = e.pre(r0 + 16 * ra + fr, c0 + 32 * np + 8 * fq); } }
;     f32x4 acc[RA][NP][2];
; #pragma unroll
;     for (int ra = 0; ra < RA; ++ra)
; #pragma unroll
;         for (int np = 0; np < NP; ++np) { acc[ra][np][0] = (f32x4){0.f, 0.f, 0.f, 0.f}; acc[ra][np][1] = (f32x4){0.f, 0.f, 0.f, 0.f}; }
;     int aoff[RA], boff[NP][2];
; #pragma unroll
;     for (int ra = 0; ra < RA; ++ra) aoff[ra] = pg8::lds_byte(16 * (wr * RA + ra) + fr, 8 * fq);
; #pragma unroll
;     for (int np = 0; np < NP; ++np)
; #pragma unroll
;         for (int n = 0; n < 2; ++n) { const int rb = wc * (32 * NP) + 32 * np + 16 * n + fr; boff[np][n] = 8192 * (1 + (rb >> 6)) + pg8::lds_byte(rb & 63, 8 * fq); }
; #pragma unroll
;     for (int s = 0; s < NS - 1; ++s) SG_STAGE(s, s);
.LBB0_1499:
	s_lshl_b32 s3, s3, 2
	s_andn2_b32 s3, s3, 63
	s_lshl_b32 s5, s34, 6
	v_and_b32_e32 v4, 0xffffffe0, v133
	v_or_b32_e32 v6, s3, v154
	s_lshl_b32 s4, s27, 7
	s_and_b32 s5, s5, 64
	v_and_b32_e32 v5, 24, v155
	v_add_u32_e32 v4, v6, v4
	s_or_b32 s4, s5, s4
	s_lshr_b32 s5, s42, 31
	v_or3_b32 v4, v4, v5, v153
	s_bitset1_b32 s4, 14
	s_add_i32 s5, s42, s5
	v_ashrrev_i32_e32 v5, 31, v4
	s_ashr_i32 s12, s5, 1
	v_add_u32_e32 v8, s4, v133
	v_lshlrev_b64 v[4:5], 13, v[4:5]
	v_ashrrev_i32_e32 v9, 31, v8
	v_lshl_add_u64 v[4:5], s[10:11], 0, v[4:5]
	s_lshl_b32 s10, s12, 4
	v_ashrrev_i32_e32 v133, 31, v132
	s_add_i32 s4, s4, s10
	v_lshlrev_b64 v[8:9], 13, v[8:9]
	v_lshlrev_b64 v[10:11], 1, v[132:133]
	v_or_b32_e32 v16, s4, v152
	v_lshl_add_u64 v[8:9], s[6:7], 0, v[8:9]
	s_add_i32 s4, s43, 0
	v_lshl_add_u64 v[22:23], v[8:9], 0, v[10:11]
	s_mov_b32 m0, s4
	v_lshl_add_u64 v[20:21], v[4:5], 0, v[10:11]
	s_nop 0
	s_add_i32 m0, s4, 0x2000
	v_lshl_add_u64 v[8:9], v[22:23], 0, s[52:53]
	s_nop 0
	s_add_i32 m0, s4, 0x4000
	s_mov_b64 s[6:7], 0x100
	s_nop 0
	v_lshl_add_u64 v[8:9], v[20:21], 0, s[52:53]
	s_add_i32 m0, s4, 0x6000
	s_and_b32 s5, s5, -2
	s_nop 0
	s_add_i32 m0, s4, 0x8000
	v_lshl_add_u64 v[8:9], v[22:23], 0, s[6:7]
	s_sub_i32 s5, s42, s5
	s_nop 0
	v_lshl_add_u64 v[8:9], v[20:21], 0, s[6:7]
	s_add_i32 m0, s4, 0xa000
	s_mov_b64 s[6:7], 0x180
	s_lshl_b32 s10, s5, 5
	s_nop 0
	v_lshl_add_u64 v[8:9], v[22:23], 0, s[6:7]
	s_add_i32 m0, s4, 0xc000
	s_add_i32 s3, s10, s3
	v_lshrrev_b32_e32 v4, 1, v3
	v_ashrrev_i32_e32 v17, 31, v16
	s_nop 0
	v_lshl_add_u64 v[8:9], v[20:21], 0, s[6:7]
	s_add_i32 m0, s4, 0xe000
	v_and_or_b32 v4, v4, 24, s3
	v_lshlrev_b64 v[6:7], 11, v[16:17]
	s_nop 0
	s_add_i32 m0, s4, 0x10000
	v_lshl_add_u64 v[8:9], v[22:23], 0, s[54:55]
	v_lshl_add_u64 v[6:7], s[8:9], 0, v[6:7]
	v_ashrrev_i32_e32 v5, 31, v4
	s_nop 0
	v_lshl_add_u64 v[8:9], v[20:21], 0, s[54:55]
	s_add_i32 m0, s4, 0x12000
	s_mov_b64 s[6:7], 0x280
	v_lshl_add_u64 v[18:19], v[4:5], 1, v[6:7]
	s_nop 0
	v_lshl_add_u64 v[8:9], v[22:23], 0, s[6:7]
	s_add_i32 m0, s4, 0x14000
	global_load_dwordx4 v[4:7], v[18:19], off
	v_and_b32_e32 v24, 63, v3
	s_nop 0
	v_lshl_add_u64 v[8:9], v[20:21], 0, s[6:7]
	s_add_i32 m0, s4, 0x16000
	v_lshlrev_b32_e32 v11, 6, v3
	s_nop 0
	v_and_b32_e32 v8, 48, v3
	v_lshlrev_b32_e32 v3, 2, v3
	v_lshlrev_b32_e32 v10, 2, v152
	s_and_b32 s6, s5, 0xffffe000
	v_and_b32_e32 v11, 0x3c0, v11
	s_lshl_b32 s5, s5, 12
	v_and_b32_e32 v3, 32, v3
	v_lshlrev_b32_e32 v9, 6, v152
	v_and_b32_e32 v10, 32, v10
	s_and_b32 s5, s5, 0x1000
	v_bitop3_b32 v3, v11, v3, v8 bitop3:0x36
	v_or_b32_e32 v11, s5, v3
	v_bitop3_b32 v3, v9, v10, v8 bitop3:0x36
	v_mov_b32_e32 v8, 0
	s_mov_b64 s[86:87], 0x100
	s_lshl_b32 s5, s12, 11
	v_or_b32_e32 v25, s6, v11
	s_movk_i32 s6, 0x180
	s_mov_b32 s7, 0
	v_mov_b32_e32 v9, v8
	v_mov_b32_e32 v10, v8
	v_mov_b32_e32 v11, v8
	v_mov_b32_e32 v12, v8
	v_mov_b32_e32 v13, v8
	v_mov_b32_e32 v14, v8
	v_mov_b32_e32 v15, v8
